# GLA pass3: second-direction state fragments and gate/key rows prefetched before the direction loop
# baseline (speedup 1.0000x reference)
.LBB0_734:
	s_abs_i32 s1, s74
	v_readlane_b32 s2, v255, 40
	s_mul_hi_u32 s2, s1, s2
	s_mul_i32 s3, s2, s41
	s_sub_i32 s1, s1, s3
	s_ashr_i32 s0, s74, 31
	s_add_i32 s3, s2, 1
	s_sub_i32 s8, s1, s41
	s_cmp_ge_u32 s1, s41
	s_cselect_b32 s2, s3, s2
	s_cselect_b32 s1, s8, s1
	s_add_i32 s3, s2, 1
	s_cmp_ge_u32 s1, s41
	s_cselect_b32 s1, s3, s2
	s_xor_b32 s1, s1, s0
	s_sub_i32 s1, s1, s0
	s_and_b32 s0, s1, 3
	s_ashr_i32 s1, s1, 2
	s_sub_i32 s75, 1, s1
	s_lshl_b32 s2, s21, 6
	v_mov_b32_e32 v10, v207
	s_cmp_lt_i32 s21, 4
	s_cselect_b32 s22, s7, s6
	v_lshlrev_b32_e32 v0, 4, v10
	v_and_b32_e32 v66, 0x70, v0
	s_add_i32 s22, s22, s2
	v_mov_b32_e32 v0, v207
	s_barrier
	s_cmp_lg_u32 s1, 1
	v_and_b32_e32 v6, 63, v0
	v_or_b32_e32 v1, s22, v6
	s_movk_i32 s2, 0x1200
	s_cselect_b64 s[96:97], -1, 0
	s_lshl_b32 s20, s0, 7
	s_lshl_b32 s26, s0, 8
	v_mul_lo_u32 v128, v1, s2
	s_cmp_eq_u32 s1, 1
	s_movk_i32 s1, 0x800
	v_ashrrev_i32_e32 v0, 2, v0
	v_lshl_add_u64 v[2:3], v[128:129], 1, s[36:37]
	s_cselect_b32 s94, s1, 0x1c00
	s_mov_b32 s95, 0
	v_and_b32_e32 v0, -16, v0
	v_lshl_add_u64 v[2:3], v[2:3], 0, s[94:95]
	v_lshl_add_u64 v[2:3], v[2:3], 0, s[26:27]
	v_ashrrev_i32_e32 v1, 31, v0
	v_lshl_add_u64 v[4:5], v[0:1], 1, v[2:3]
	s_movk_i32 s8, 0x90
	v_lshlrev_b32_e32 v12, 1, v6
	v_mul_lo_u32 v13, v0, s8
	global_load_dwordx4 v[0:3], v[4:5], off
	s_nop 0
	global_load_dwordx4 v[4:7], v[4:5], off offset:16
	v_ashrrev_i32_e32 v67, 3, v10
	v_mov_b64_e32 v[8:9], s[36:37]
	v_readlane_b32 s4, v252, 12
	v_add_u32_e32 v64, s22, v67
	v_mad_i64_i32 v[68:69], s[2:3], v64, s14, v[8:9]
	v_add3_u32 v14, s4, v12, v13
	v_add3_u32 v12, s4, v13, v12
	s_cselect_b32 s94, 0, 0x1000
	v_lshlrev_b32_e32 v128, 1, v66
	v_ashrrev_i32_e32 v11, 6, v10
	v_and_b32_e32 v92, 31, v10
	v_and_b32_e32 v94, 3, v11
	s_lshl_b32 s1, s75, 3
	s_lshl_b32 s2, s0, 1
	s_or_b32 s23, s1, s2
	v_bfe_u32 v93, v10, 5, 1
	s_cmp_gt_i32 s21, 3
	s_cselect_b32 s1, 0x87, 3
	v_lshl_add_u32 v95, v66, 2, 0
	v_readlane_b32 s5, v255, 1
	v_bfi_b32 v8, -16, v67, v10
	v_cvt_f32_ubyte0_e32 v96, s0
	v_ashrrev_i32_e32 v65, 31, v64
	s_mov_b64 s[92:93], -1
	v_lshl_add_u64 v[162:163], v[68:69], 0, s[94:95]
	v_lshl_add_u64 v[162:163], v[162:163], 0, s[26:27]
	v_lshl_add_u64 v[162:163], v[162:163], 0, v[128:129]
	global_load_dwordx4 v[154:157], v[162:163], off
	global_load_dwordx4 v[158:161], v[162:163], off offset:16
	s_waitcnt vmcnt(0) lgkmcnt(0)
	ds_write_b16 v14, v0
	ds_write_b16_d16_hi v12, v0 offset:144
	ds_write_b16 v14, v1 offset:288
	ds_write_b16_d16_hi v12, v1 offset:432
	ds_write_b16 v14, v2 offset:576
	ds_write_b16_d16_hi v12, v2 offset:720
	ds_write_b16 v14, v3 offset:864
	ds_write_b16_d16_hi v12, v3 offset:1008
	ds_write_b16 v14, v4 offset:1152
	ds_write_b16_d16_hi v12, v4 offset:1296
	ds_write_b16 v14, v5 offset:1440
	ds_write_b16_d16_hi v12, v5 offset:1584
	ds_write_b16 v14, v6 offset:1728
	ds_write_b16_d16_hi v12, v6 offset:1872
	ds_write_b16 v14, v7 offset:2016
	ds_write_b16_d16_hi v12, v7 offset:2160
	v_lshl_add_u64 v[0:1], v[68:69], 0, s[94:95]
	v_lshl_add_u64 v[0:1], v[0:1], 0, s[26:27]
	v_lshl_add_u64 v[4:5], v[0:1], 0, v[128:129]
	s_sub_i32 s94, s1, s21
	v_readlane_b32 s1, v255, 0
	s_add_u32 s2, s36, s26
	s_addc_u32 s3, s37, 0
	s_waitcnt vmcnt(0) lgkmcnt(0)
	v_lshlrev_b32_e32 v70, 16, v154
	v_lshlrev_b32_e32 v78, 16, v158
	v_and_b32_e32 v79, 0xffff0000, v158
	v_lshl_or_b32 v4, v94, 5, v92
	v_and_b32_e32 v71, 0xffff0000, v154
	v_lshlrev_b32_e32 v72, 16, v155
	v_and_b32_e32 v73, 0xffff0000, v155
	v_lshlrev_b32_e32 v0, 8, v4
	v_mov_b32_e32 v1, v129
	v_lshlrev_b32_e32 v74, 16, v156
	v_and_b32_e32 v75, 0xffff0000, v156
	v_lshlrev_b32_e32 v76, 16, v157
	v_and_b32_e32 v77, 0xffff0000, v157
	v_lshl_add_u64 v[0:1], s[84:85], 0, v[0:1]
	v_lshlrev_b32_e32 v2, 4, v93
	v_mov_b32_e32 v3, v129
	v_lshl_add_u64 v[86:87], v[0:1], 0, v[2:3]
	v_add_u32_e32 v3, s4, v2
	s_movk_i32 s4, 0x110
	v_lshlrev_b32_e32 v80, 16, v159
	v_and_b32_e32 v81, 0xffff0000, v159
	v_sub_u32_e32 v0, v95, v128
	v_add_u32_e32 v1, s5, v2
	v_add_u32_e32 v5, s1, v2
	v_mul_lo_u32 v2, v67, s4
	v_add_u32_e32 v97, v0, v2
	v_add3_u32 v98, s1, v128, v2
	v_and_b32_e32 v2, 48, v10
	v_add_u32_e32 v2, 0, v2
	v_mad_u64_u32 v[88:89], s[0:1], v8, s4, v[2:3]
	v_lshrrev_b32_e32 v8, 2, v10
	v_and_b32_e32 v8, 12, v8
	v_lshlrev_b32_e32 v84, 16, v161
	v_and_b32_e32 v85, 0xffff0000, v161
	v_lshlrev_b32_e32 v0, 5, v11
	v_and_b32_e32 v7, 15, v10
	v_and_or_b32 v8, v67, -16, v8
	v_and_or_b32 v0, v0, 32, v7
	v_or_b32_e32 v13, 1, v8
	v_or_b32_e32 v14, 2, v8
	v_or_b32_e32 v15, 3, v8
	s_movk_i32 s0, 0xffe0
	v_mul_u32_u24_e32 v7, 0x110, v0
	v_lshl_add_u32 v11, v0, 1, s5
	v_cmp_ge_i32_e64 s[42:43], v0, v8
	v_cmp_le_i32_e64 s[44:45], v0, v8
	v_cmp_gt_i32_e64 s[46:47], v0, v8
	v_cmp_le_i32_e64 s[48:49], v0, v13
	v_cmp_ge_i32_e64 s[50:51], v0, v14
	v_cmp_le_i32_e64 s[52:53], v0, v14
	v_cmp_ge_i32_e64 s[54:55], v0, v15
	v_cmp_le_i32_e64 s[56:57], v0, v15
	v_or_b32_e32 v0, 16, v0
	v_bfi_b32 v9, s0, v67, v10
	v_mul_lo_u32 v12, v8, s8
	v_lshlrev_b32_e32 v16, 1, v0
	v_lshlrev_b32_e32 v82, 16, v160
	v_and_b32_e32 v83, 0xffff0000, v160
	v_lshlrev_b32_e32 v6, 9, v67
	v_mul_lo_u32 v10, v9, s8
	v_mul_u32_u24_e32 v4, 0x90, v4
	v_mul_lo_u32 v9, v9, s4
	v_cmp_ge_i32_e64 s[58:59], v0, v8
	v_cmp_le_i32_e64 s[60:61], v0, v8
	v_add3_u32 v99, s5, v12, v16
	v_cmp_gt_i32_e64 s[62:63], v0, v8
	v_cmp_le_i32_e64 s[64:65], v0, v13
	v_cmp_ge_i32_e64 s[66:67], v0, v14
	v_cmp_le_i32_e64 s[68:69], v0, v14
	v_cmp_ge_i32_e64 s[70:71], v0, v15
	v_cmp_le_i32_e64 s[72:73], v0, v15
	v_mov_b32_e32 v0, 0
	v_and_b32_e32 v89, 0xffffffe0, v67
	v_add_u32_e32 v100, 0x90, v99
	v_add_u32_e32 v101, 0x120, v99
	v_add_u32_e32 v102, 0x1b0, v99
	v_add_u32_e32 v103, v95, v6
	v_add_u32_e32 v104, v2, v7
	v_add_u32_e32 v105, v11, v12
	v_add_u32_e32 v106, v1, v10
	v_add_u32_e32 v107, v3, v4
	v_add_u32_e32 v108, v5, v9
	v_mov_b32_e32 v1, v0
	v_mov_b32_e32 v2, v0
	v_mov_b32_e32 v3, v0
	v_mov_b32_e32 v4, v0
	v_mov_b32_e32 v5, v0
	v_mov_b32_e32 v6, v0
	v_mov_b32_e32 v7, v0
	v_mov_b32_e32 v8, v0
	v_mov_b32_e32 v9, v0
	v_mov_b32_e32 v10, v0
	v_mov_b32_e32 v11, v0
	v_mov_b32_e32 v12, v0
	v_mov_b32_e32 v13, v0
	v_mov_b32_e32 v14, v0
	v_mov_b32_e32 v15, v0
	s_or_b32 s0, 1, s23
	s_mul_hi_i32 s8, s0, 0x84
	s_mul_i32 s9, s0, 0x84
	s_ashr_i32 s1, s94, 31
	s_add_u32 s0, s9, s94
	s_addc_u32 s1, s8, s1
	s_lshl_b64 s[0:1], s[0:1], 15
	v_lshl_add_u64 v[244:245], v[86:87], 0, s[0:1]
	global_load_dwordx4 v[188:191], v[244:245], off
	global_load_dwordx4 v[194:197], v[244:245], off offset:32
	global_load_dwordx4 v[200:203], v[244:245], off offset:64
	global_load_dwordx4 v[208:211], v[244:245], off offset:96
	global_load_dwordx4 v[212:215], v[244:245], off offset:128
	global_load_dwordx4 v[216:219], v[244:245], off offset:160
	global_load_dwordx4 v[224:227], v[244:245], off offset:192
	global_load_dwordx4 v[240:243], v[244:245], off offset:224
	s_lshl_b32 s0, s20, 1
	s_and_b64 s[8:9], s[96:97], exec
	s_movk_i32 s1, 0x400
	s_cselect_b32 s1, 0x1800, s1
	s_add_i32 s0, s0, s1
	s_mov_b32 s1, 0
	v_lshlrev_b32_e32 v246, 1, v66
	v_mov_b32_e32 v247, 0
	v_lshl_add_u64 v[246:247], v[68:69], 0, v[246:247]
	v_lshl_add_u64 v[246:247], v[246:247], 0, s[0:1]
	global_load_dwordx4 v[180:183], v[246:247], off
	global_load_dwordx4 v[184:187], v[246:247], off offset:16
	s_branch .LBB0_736

.LBB0_736:
	s_xor_b64 s[18:19], s[92:93], -1
	s_or_b32 s0, s95, s23
	s_mul_hi_i32 s8, s0, 0x84
	s_mul_i32 s9, s0, 0x84
	s_and_b64 s[0:1], s[92:93], exec
	s_cselect_b32 s0, s21, s94
	s_ashr_i32 s1, s0, 31
	s_add_u32 s0, s9, s0
	s_addc_u32 s1, s8, s1
	s_lshl_b64 s[0:1], s[0:1], 15
	v_lshl_add_u64 v[16:17], v[86:87], 0, s[0:1]
	s_cmp_eq_u32 s95, 0
	s_cbranch_scc0 .Lp3_dir1_sfr
	global_load_dwordx4 v[60:63], v[16:17], off
	global_load_dwordx4 v[56:59], v[16:17], off offset:32
	global_load_dwordx4 v[52:55], v[16:17], off offset:64
	global_load_dwordx4 v[48:51], v[16:17], off offset:96
	global_load_dwordx4 v[44:47], v[16:17], off offset:128
	global_load_dwordx4 v[40:43], v[16:17], off offset:160
	global_load_dwordx4 v[36:39], v[16:17], off offset:192
	global_load_dwordx4 v[32:35], v[16:17], off offset:224
	s_branch .Lp3_sfr_done
.Lp3_dir1_sfr:
	s_waitcnt vmcnt(0)
	v_mov_b32_e32 v60, v188
	v_mov_b32_e32 v61, v189
	v_mov_b32_e32 v62, v190
	v_mov_b32_e32 v63, v191
	v_mov_b32_e32 v56, v194
	v_mov_b32_e32 v57, v195
	v_mov_b32_e32 v58, v196
	v_mov_b32_e32 v59, v197
	v_mov_b32_e32 v52, v200
	v_mov_b32_e32 v53, v201
	v_mov_b32_e32 v54, v202
	v_mov_b32_e32 v55, v203
	v_mov_b32_e32 v48, v208
	v_mov_b32_e32 v49, v209
	v_mov_b32_e32 v50, v210
	v_mov_b32_e32 v51, v211
	v_mov_b32_e32 v44, v212
	v_mov_b32_e32 v45, v213
	v_mov_b32_e32 v46, v214
	v_mov_b32_e32 v47, v215
	v_mov_b32_e32 v40, v216
	v_mov_b32_e32 v41, v217
	v_mov_b32_e32 v42, v218
	v_mov_b32_e32 v43, v219
	v_mov_b32_e32 v36, v224
	v_mov_b32_e32 v37, v225
	v_mov_b32_e32 v38, v226
	v_mov_b32_e32 v39, v227
	v_mov_b32_e32 v32, v240
	v_mov_b32_e32 v33, v241
	v_mov_b32_e32 v34, v242
	v_mov_b32_e32 v35, v243
.Lp3_sfr_done:
	v_mov_b32_e32 v113, v207
	s_and_b64 vcc, exec, s[96:97]
	v_ashrrev_i32_e32 v110, 3, v113
	v_lshlrev_b32_e32 v16, 4, v113
	v_and_b32_e32 v111, 0x70, v16
	v_add_u32_e32 v18, s22, v110
	v_mov_b64_e32 v[16:17], s[2:3]
	v_mad_i64_i32 v[16:17], s[0:1], v18, s14, v[16:17]
	v_lshlrev_b32_e32 v128, 1, v111
	v_lshl_add_u64 v[90:91], v[16:17], 0, v[128:129]
	v_lshlrev_b32_e32 v16, 9, v110
	v_lshlrev_b32_e32 v17, 2, v111
	v_add3_u32 v109, 0, v16, v17
	s_mov_b64 s[0:1], -1
	s_cbranch_vccz .LBB0_754
	s_and_b64 s[0:1], s[92:93], exec
	s_cselect_b32 s26, s15, 0x1800
	v_lshl_add_u64 v[20:21], v[90:91], 0, s[26:27]
	s_cbranch_scc0 .Lp3_x1
	global_load_dwordx4 v[16:19], v[20:21], off
	global_load_dwordx4 v[116:119], v[20:21], off offset:16
	s_branch .Lp3_xdone
.Lp3_x1:
	s_waitcnt vmcnt(0)
	v_mov_b32_e32 v16, v180
	v_mov_b32_e32 v17, v181
	v_mov_b32_e32 v18, v182
	v_mov_b32_e32 v19, v183
	v_mov_b32_e32 v116, v184
	v_mov_b32_e32 v117, v185
	v_mov_b32_e32 v118, v186
	v_mov_b32_e32 v119, v187
.Lp3_xdone:
	s_waitcnt vmcnt(0) lgkmcnt(0)
	v_lshlrev_b32_e32 v20, 16, v16
	v_and_b32_e32 v112, 0xffff0000, v16
	v_or_b32_e32 v16, s20, v111
	v_lshlrev_b32_e32 v128, 2, v16
	v_lshlrev_b32_e32 v115, 16, v17
	v_and_b32_e32 v120, 0xffff0000, v17
	v_lshl_add_u64 v[16:17], s[78:79], 0, v[128:129]
	global_load_dword v111, v[16:17], off
	v_lshlrev_b32_e32 v31, 16, v19
	v_and_b32_e32 v30, 0xffff0000, v19
	v_mul_f32_e32 v19, 0xbfb8aa3b, v20
	v_exp_f32_e32 v19, v19
	v_lshlrev_b32_e32 v29, 16, v116
	v_and_b32_e32 v28, 0xffff0000, v116
	v_lshlrev_b32_e32 v27, 16, v117
	v_add_f32_e32 v19, 1.0, v19
	v_rcp_f32_e32 v116, v19
	v_and_b32_e32 v26, 0xffff0000, v117
	v_lshlrev_b32_e32 v25, 16, v118
	v_and_b32_e32 v24, 0xffff0000, v118
	v_lshlrev_b32_e32 v23, 16, v119
	v_and_b32_e32 v22, 0xffff0000, v119
	v_mul_f32_e32 v19, 1.0, v116
	v_mul_f32_e32 v20, 0xbfb8aa3b, v112
	v_exp_f32_e32 v20, v20
	v_lshlrev_b32_e32 v114, 16, v18
	v_and_b32_e32 v21, 0xffff0000, v18
	v_mul_f32_e32 v114, 0xbfb8aa3b, v114
	v_add_f32_e32 v20, 1.0, v20
	v_rcp_f32_e32 v116, v20
	v_exp_f32_e32 v114, v114
	v_mul_f32_e32 v21, 0xbfb8aa3b, v21
	v_exp_f32_e32 v21, v21
	v_mul_f32_e32 v20, 1.0, v116
	v_add_f32_e32 v114, 1.0, v114
	v_add_f32_e32 v21, 1.0, v21
	v_mul_f32_e32 v31, 0xbfb8aa3b, v31
	v_exp_f32_e32 v31, v31
	v_mul_f32_e32 v30, 0xbfb8aa3b, v30
	v_exp_f32_e32 v30, v30
	v_mul_f32_e32 v29, 0xbfb8aa3b, v29
	v_add_f32_e32 v31, 1.0, v31
	v_exp_f32_e32 v29, v29
	v_add_f32_e32 v30, 1.0, v30
	v_mul_f32_e32 v28, 0xbfb8aa3b, v28
	v_exp_f32_e32 v28, v28
	v_add_f32_e32 v29, 1.0, v29
	v_mul_f32_e32 v27, 0xbfb8aa3b, v27
	v_exp_f32_e32 v27, v27
	v_add_f32_e32 v28, 1.0, v28
	v_mul_f32_e32 v26, 0xbfb8aa3b, v26
	v_exp_f32_e32 v26, v26
	v_add_f32_e32 v27, 1.0, v27
	v_mul_f32_e32 v25, 0xbfb8aa3b, v25
	v_exp_f32_e32 v25, v25
	v_add_f32_e32 v26, 1.0, v26
	v_mul_f32_e32 v24, 0xbfb8aa3b, v24
	v_exp_f32_e32 v24, v24
	v_add_f32_e32 v25, 1.0, v25
	v_mul_f32_e32 v23, 0xbfb8aa3b, v23
	v_exp_f32_e32 v23, v23
	v_add_f32_e32 v24, 1.0, v24
	v_mul_f32_e32 v22, 0xbfb8aa3b, v22
	v_exp_f32_e32 v22, v22
	v_add_f32_e32 v23, 1.0, v23
	s_waitcnt vmcnt(0) lgkmcnt(0)
	v_sub_f32_e32 v18, 1.0, v111
	v_fmac_f32_e32 v111, v18, v19
	v_cmp_gt_f32_e32 vcc, s12, v111
	v_add_f32_e32 v22, 1.0, v22
	s_nop 0
	v_cndmask_b32_e64 v18, 0, 32, vcc
	v_ldexp_f32 v18, v111, v18
	v_log_f32_e32 v18, v18
	s_nop 0
	v_mul_f32_e32 v19, 0x3f317217, v18
	v_fma_f32 v19, v18, s86, -v19
	v_fmac_f32_e32 v19, 0x3377d1cf, v18
	v_fmac_f32_e32 v19, 0x3f317217, v18
	v_cmp_lt_f32_e64 s[0:1], |v18|, s87
	s_nop 1
	v_cndmask_b32_e64 v18, v18, v19, s[0:1]
	v_cndmask_b32_e32 v19, 0, v231, vcc
	v_sub_f32_e32 v18, v18, v19
	ds_write_b32 v109, v18
	global_load_dword v112, v[16:17], off offset:4
	s_waitcnt vmcnt(0) lgkmcnt(0)
	v_sub_f32_e32 v18, 1.0, v112
	v_fmac_f32_e32 v112, v18, v20
	v_cmp_gt_f32_e32 vcc, s12, v112
	v_mul_f32_e32 v20, 0xbfb8aa3b, v115
	v_exp_f32_e32 v20, v20
	v_cndmask_b32_e64 v18, 0, 32, vcc
	v_ldexp_f32 v18, v112, v18
	v_log_f32_e32 v18, v18
	v_add_f32_e32 v20, 1.0, v20
	v_mul_f32_e32 v19, 0x3f317217, v18
	v_fma_f32 v19, v18, s86, -v19
	v_fmac_f32_e32 v19, 0x3377d1cf, v18
	v_fmac_f32_e32 v19, 0x3f317217, v18
	v_cmp_lt_f32_e64 s[0:1], |v18|, s87
	s_nop 1
	v_cndmask_b32_e64 v18, v18, v19, s[0:1]
	v_cndmask_b32_e32 v19, 0, v231, vcc
	v_sub_f32_e32 v18, v18, v19
	ds_write_b32 v109, v18 offset:4
	global_load_dword v18, v[16:17], off offset:8
	v_rcp_f32_e32 v116, v20
	s_waitcnt vmcnt(0) lgkmcnt(0)
	v_sub_f32_e32 v19, 1.0, v18
	v_mul_f32_e32 v20, 1.0, v116
	v_mul_f32_e32 v115, 0xbfb8aa3b, v120
	v_exp_f32_e32 v115, v115
	v_fmac_f32_e32 v18, v20, v19
	v_add_f32_e32 v115, 1.0, v115
	v_rcp_f32_e32 v117, v115
	s_nop 0
	v_cmp_gt_f32_e32 vcc, s12, v18
	v_mul_f32_e32 v115, 1.0, v117
	s_nop 0
	v_cndmask_b32_e64 v19, 0, 32, vcc
	v_ldexp_f32 v19, v18, v19
	v_log_f32_e32 v19, v19
	s_nop 0
	v_mul_f32_e32 v20, 0x3f317217, v19
	v_fma_f32 v20, v19, s86, -v20
	v_fmac_f32_e32 v20, 0x3377d1cf, v19
	v_fmac_f32_e32 v20, 0x3f317217, v19
	v_cmp_lt_f32_e64 s[0:1], |v19|, s87
	s_nop 1
	v_cndmask_b32_e64 v19, v19, v20, s[0:1]
	v_cndmask_b32_e32 v20, 0, v231, vcc
	v_sub_f32_e32 v19, v19, v20
	ds_write_b32 v109, v19 offset:8
	global_load_dword v19, v[16:17], off offset:12
	s_waitcnt vmcnt(0) lgkmcnt(0)
	v_sub_f32_e32 v20, 1.0, v19
	v_fmac_f32_e32 v19, v115, v20
	v_cmp_gt_f32_e32 vcc, s12, v19
	s_nop 1
	v_cndmask_b32_e64 v20, 0, 32, vcc
	v_ldexp_f32 v20, v19, v20
	v_log_f32_e32 v20, v20
	s_nop 0
	v_mul_f32_e32 v115, 0x3f317217, v20
	v_fma_f32 v115, v20, s86, -v115
	v_fmac_f32_e32 v115, 0x3377d1cf, v20
	v_fmac_f32_e32 v115, 0x3f317217, v20
	v_cmp_lt_f32_e64 s[0:1], |v20|, s87
	s_nop 1
	v_cndmask_b32_e64 v20, v20, v115, s[0:1]
	v_cndmask_b32_e32 v115, 0, v231, vcc
	v_sub_f32_e32 v20, v20, v115
	ds_write_b32 v109, v20 offset:12
	global_load_dword v20, v[16:17], off offset:16
	v_rcp_f32_e32 v117, v114
	s_waitcnt vmcnt(0) lgkmcnt(0)
	v_sub_f32_e32 v115, 1.0, v20
	v_mul_f32_e32 v114, 1.0, v117
	v_rcp_f32_e32 v117, v21
	v_fmac_f32_e32 v20, v114, v115
	v_cmp_gt_f32_e32 vcc, s12, v20
	v_mul_f32_e32 v116, 1.0, v117
	s_nop 0
	v_cndmask_b32_e64 v21, 0, 32, vcc
	v_ldexp_f32 v21, v20, v21
	v_log_f32_e32 v21, v21
	s_nop 0
	v_mul_f32_e32 v114, 0x3f317217, v21
	v_fma_f32 v114, v21, s86, -v114
	v_fmac_f32_e32 v114, 0x3377d1cf, v21
	v_fmac_f32_e32 v114, 0x3f317217, v21
	v_cmp_lt_f32_e64 s[0:1], |v21|, s87
	s_nop 1
	v_cndmask_b32_e64 v21, v21, v114, s[0:1]
	v_cndmask_b32_e32 v114, 0, v231, vcc
	v_sub_f32_e32 v21, v21, v114
	ds_write_b32 v109, v21 offset:16
	global_load_dword v21, v[16:17], off offset:20
	s_waitcnt vmcnt(0) lgkmcnt(0)
	v_sub_f32_e32 v114, 1.0, v21
	v_fmac_f32_e32 v21, v116, v114
	v_cmp_gt_f32_e32 vcc, s12, v21
	s_nop 1
	v_cndmask_b32_e64 v114, 0, 32, vcc
	v_ldexp_f32 v114, v21, v114
	v_log_f32_e32 v114, v114
	s_nop 0
	v_mul_f32_e32 v115, 0x3f317217, v114
	v_fma_f32 v115, v114, s86, -v115
	v_fmac_f32_e32 v115, 0x3377d1cf, v114
	v_fmac_f32_e32 v115, 0x3f317217, v114
	v_cmp_lt_f32_e64 s[0:1], |v114|, s87
	s_nop 1
	v_cndmask_b32_e64 v114, v114, v115, s[0:1]
	v_cndmask_b32_e32 v115, 0, v231, vcc
	v_sub_f32_e32 v114, v114, v115
	ds_write_b32 v109, v114 offset:20
	global_load_dword v114, v[16:17], off offset:24
	v_rcp_f32_e32 v117, v31
	s_waitcnt vmcnt(0) lgkmcnt(0)
	v_sub_f32_e32 v115, 1.0, v114
	v_mul_f32_e32 v31, 1.0, v117
	v_rcp_f32_e32 v117, v30
	v_fmac_f32_e32 v114, v31, v115
	v_cmp_gt_f32_e32 vcc, s12, v114
	v_mul_f32_e32 v30, 1.0, v117
	s_nop 0
	v_cndmask_b32_e64 v31, 0, 32, vcc
	v_ldexp_f32 v31, v114, v31
	v_log_f32_e32 v31, v31
	s_nop 0
	v_mul_f32_e32 v115, 0x3f317217, v31
	v_fma_f32 v115, v31, s86, -v115
	v_fmac_f32_e32 v115, 0x3377d1cf, v31
	v_fmac_f32_e32 v115, 0x3f317217, v31
	v_cmp_lt_f32_e64 s[0:1], |v31|, s87
	s_nop 1
	v_cndmask_b32_e64 v31, v31, v115, s[0:1]
	v_cndmask_b32_e32 v115, 0, v231, vcc
	v_sub_f32_e32 v31, v31, v115
	ds_write_b32 v109, v31 offset:24
	global_load_dword v115, v[16:17], off offset:28
	s_waitcnt vmcnt(0) lgkmcnt(0)
	v_sub_f32_e32 v31, 1.0, v115
	v_fmac_f32_e32 v115, v30, v31
	v_cmp_gt_f32_e32 vcc, s12, v115
	s_nop 1
	v_cndmask_b32_e64 v30, 0, 32, vcc
	v_ldexp_f32 v30, v115, v30
	v_log_f32_e32 v30, v30
	s_nop 0
	v_mul_f32_e32 v31, 0x3f317217, v30
	v_fma_f32 v31, v30, s86, -v31
	v_fmac_f32_e32 v31, 0x3377d1cf, v30
	v_fmac_f32_e32 v31, 0x3f317217, v30
	v_cmp_lt_f32_e64 s[0:1], |v30|, s87
	s_nop 1
	v_cndmask_b32_e64 v30, v30, v31, s[0:1]
	v_cndmask_b32_e32 v31, 0, v231, vcc
	v_sub_f32_e32 v30, v30, v31
	ds_write_b32 v109, v30 offset:28
	global_load_dword v116, v[16:17], off offset:32
	v_rcp_f32_e32 v117, v29
	s_waitcnt vmcnt(0) lgkmcnt(0)
	v_sub_f32_e32 v30, 1.0, v116
	v_mul_f32_e32 v29, 1.0, v117
	v_rcp_f32_e32 v117, v28
	v_fmac_f32_e32 v116, v29, v30
	v_cmp_gt_f32_e32 vcc, s12, v116
	v_mul_f32_e32 v28, 1.0, v117
	s_nop 0
	v_cndmask_b32_e64 v29, 0, 32, vcc
	v_ldexp_f32 v29, v116, v29
	v_log_f32_e32 v29, v29
	s_nop 0
	v_mul_f32_e32 v30, 0x3f317217, v29
	v_fma_f32 v30, v29, s86, -v30
	v_fmac_f32_e32 v30, 0x3377d1cf, v29
	v_fmac_f32_e32 v30, 0x3f317217, v29
	v_cmp_lt_f32_e64 s[0:1], |v29|, s87
	s_nop 1
	v_cndmask_b32_e64 v29, v29, v30, s[0:1]
	v_cndmask_b32_e32 v30, 0, v231, vcc
	v_sub_f32_e32 v29, v29, v30
	ds_write_b32 v109, v29 offset:32
	global_load_dword v117, v[16:17], off offset:36
	s_waitcnt vmcnt(0) lgkmcnt(0)
	v_sub_f32_e32 v29, 1.0, v117
	v_fmac_f32_e32 v117, v28, v29
	v_cmp_gt_f32_e32 vcc, s12, v117
	s_nop 1
	v_cndmask_b32_e64 v28, 0, 32, vcc
	v_ldexp_f32 v28, v117, v28
	v_log_f32_e32 v28, v28
	s_nop 0
	v_mul_f32_e32 v29, 0x3f317217, v28
	v_fma_f32 v29, v28, s86, -v29
	v_fmac_f32_e32 v29, 0x3377d1cf, v28
	v_fmac_f32_e32 v29, 0x3f317217, v28
	v_cmp_lt_f32_e64 s[0:1], |v28|, s87
	s_nop 1
	v_cndmask_b32_e64 v28, v28, v29, s[0:1]
	v_cndmask_b32_e32 v29, 0, v231, vcc
	v_sub_f32_e32 v28, v28, v29
	ds_write_b32 v109, v28 offset:36
	global_load_dword v118, v[16:17], off offset:40
	v_rcp_f32_e32 v30, v27
	s_waitcnt vmcnt(0) lgkmcnt(0)
	v_sub_f32_e32 v28, 1.0, v118
	v_mul_f32_e32 v27, 1.0, v30
	v_rcp_f32_e32 v30, v26
	v_fmac_f32_e32 v118, v27, v28
	v_cmp_gt_f32_e32 vcc, s12, v118
	v_mul_f32_e32 v29, 1.0, v30
	s_nop 0
	v_cndmask_b32_e64 v26, 0, 32, vcc
	v_ldexp_f32 v26, v118, v26
	v_log_f32_e32 v26, v26
	s_nop 0
	v_mul_f32_e32 v27, 0x3f317217, v26
	v_fma_f32 v27, v26, s86, -v27
	v_fmac_f32_e32 v27, 0x3377d1cf, v26
	v_fmac_f32_e32 v27, 0x3f317217, v26
	v_cmp_lt_f32_e64 s[0:1], |v26|, s87
	s_nop 1
	v_cndmask_b32_e64 v26, v26, v27, s[0:1]
	v_cndmask_b32_e32 v27, 0, v231, vcc
	v_sub_f32_e32 v26, v26, v27
	ds_write_b32 v109, v26 offset:40
	global_load_dword v26, v[16:17], off offset:44
	s_waitcnt vmcnt(0) lgkmcnt(0)
	v_sub_f32_e32 v27, 1.0, v26
	v_fmac_f32_e32 v26, v29, v27
	v_cmp_gt_f32_e32 vcc, s12, v26
	s_nop 1
	v_cndmask_b32_e64 v27, 0, 32, vcc
	v_ldexp_f32 v27, v26, v27
	v_log_f32_e32 v27, v27
	s_nop 0
	v_mul_f32_e32 v28, 0x3f317217, v27
	v_fma_f32 v28, v27, s86, -v28
	v_fmac_f32_e32 v28, 0x3377d1cf, v27
	v_fmac_f32_e32 v28, 0x3f317217, v27
	v_cmp_lt_f32_e64 s[0:1], |v27|, s87
	s_nop 1
	v_cndmask_b32_e64 v27, v27, v28, s[0:1]
	v_cndmask_b32_e32 v28, 0, v231, vcc
	v_sub_f32_e32 v27, v27, v28
	ds_write_b32 v109, v27 offset:44
	global_load_dword v27, v[16:17], off offset:48
	v_rcp_f32_e32 v30, v25
	s_waitcnt vmcnt(0) lgkmcnt(0)
	v_sub_f32_e32 v28, 1.0, v27
	v_mul_f32_e32 v25, 1.0, v30
	v_rcp_f32_e32 v30, v24
	v_fmac_f32_e32 v27, v25, v28
	v_cmp_gt_f32_e32 vcc, s12, v27
	v_mul_f32_e32 v29, 1.0, v30
	s_nop 0
	v_cndmask_b32_e64 v24, 0, 32, vcc
	v_ldexp_f32 v24, v27, v24
	v_log_f32_e32 v24, v24
	s_nop 0
	v_mul_f32_e32 v25, 0x3f317217, v24
	v_fma_f32 v25, v24, s86, -v25
	v_fmac_f32_e32 v25, 0x3377d1cf, v24
	v_fmac_f32_e32 v25, 0x3f317217, v24
	v_cmp_lt_f32_e64 s[0:1], |v24|, s87
	s_nop 1
	v_cndmask_b32_e64 v24, v24, v25, s[0:1]
	v_cndmask_b32_e32 v25, 0, v231, vcc
	v_sub_f32_e32 v24, v24, v25
	ds_write_b32 v109, v24 offset:48
	global_load_dword v24, v[16:17], off offset:52
	s_waitcnt vmcnt(0) lgkmcnt(0)
	v_sub_f32_e32 v25, 1.0, v24
	v_fmac_f32_e32 v24, v29, v25
	v_cmp_gt_f32_e32 vcc, s12, v24
	s_nop 1
	v_cndmask_b32_e64 v25, 0, 32, vcc
	v_ldexp_f32 v25, v24, v25
	v_log_f32_e32 v25, v25
	s_nop 0
	v_mul_f32_e32 v28, 0x3f317217, v25
	v_fma_f32 v28, v25, s86, -v28
	v_fmac_f32_e32 v28, 0x3377d1cf, v25
	v_fmac_f32_e32 v28, 0x3f317217, v25
	v_cmp_lt_f32_e64 s[0:1], |v25|, s87
	s_nop 1
	v_cndmask_b32_e64 v25, v25, v28, s[0:1]
	v_cndmask_b32_e32 v28, 0, v231, vcc
	v_sub_f32_e32 v25, v25, v28
	ds_write_b32 v109, v25 offset:52
	global_load_dword v25, v[16:17], off offset:56
	v_rcp_f32_e32 v30, v23
	s_waitcnt vmcnt(0) lgkmcnt(0)
	v_sub_f32_e32 v28, 1.0, v25
	v_mul_f32_e32 v23, 1.0, v30
	v_rcp_f32_e32 v30, v22
	v_fmac_f32_e32 v25, v23, v28
	v_cmp_gt_f32_e32 vcc, s12, v25
	v_mul_f32_e32 v22, 1.0, v30
	s_nop 0
	v_cndmask_b32_e64 v23, 0, 32, vcc
	v_ldexp_f32 v23, v25, v23
	v_log_f32_e32 v23, v23
	s_nop 0
	v_mul_f32_e32 v28, 0x3f317217, v23
	v_fma_f32 v28, v23, s86, -v28
	v_fmac_f32_e32 v28, 0x3377d1cf, v23
	v_fmac_f32_e32 v28, 0x3f317217, v23
	v_cmp_lt_f32_e64 s[0:1], |v23|, s87
	s_nop 1
	v_cndmask_b32_e64 v23, v23, v28, s[0:1]
	v_cndmask_b32_e32 v28, 0, v231, vcc
	v_sub_f32_e32 v23, v23, v28
	ds_write_b32 v109, v23 offset:56
	global_load_dword v16, v[16:17], off offset:60
	s_waitcnt vmcnt(0) lgkmcnt(0)
	v_sub_f32_e32 v17, 1.0, v16
	v_fmac_f32_e32 v16, v22, v17
	v_cmp_gt_f32_e32 vcc, s12, v16
	s_nop 1
	v_cndmask_b32_e64 v17, 0, 32, vcc
	v_ldexp_f32 v17, v16, v17
	v_log_f32_e32 v17, v17
	s_nop 0
	v_mul_f32_e32 v22, 0x3f317217, v17
	v_fma_f32 v22, v17, s86, -v22
	v_fmac_f32_e32 v22, 0x3377d1cf, v17
	v_fmac_f32_e32 v22, 0x3f317217, v17
	v_cmp_lt_f32_e64 s[0:1], |v17|, s87
	s_nop 1
	v_cndmask_b32_e64 v17, v17, v22, s[0:1]
	v_cndmask_b32_e32 v22, 0, v231, vcc
	v_sub_f32_e32 v17, v17, v22
	ds_write_b32 v109, v17 offset:60
	v_ashrrev_i32_e32 v17, 7, v113
	v_and_b32_e32 v22, 0x7f, v113
	v_lshlrev_b32_e32 v23, 13, v17
	v_lshlrev_b32_e32 v28, 2, v22
	v_add3_u32 v113, 0, v28, v23
	s_mov_b64 s[0:1], -1
	s_and_b64 vcc, exec, s[18:19]
	s_waitcnt lgkmcnt(0)
	s_barrier
	s_cbranch_vccz .LBB0_739
	ds_read2st64_b32 v[30:31], v113 offset0:28 offset1:30
	s_mov_b64 s[0:1], 0
	s_waitcnt lgkmcnt(0)
	v_add_f32_e32 v29, 0, v31
	v_add_f32_e32 v119, v29, v30
	ds_read2st64_b32 v[30:31], v113 offset0:24 offset1:26
	ds_write2st64_b32 v113, v119, v29 offset0:28 offset1:30
	s_waitcnt lgkmcnt(1)
	v_add_f32_e32 v29, v119, v31
	v_add_f32_e32 v119, v29, v30
	ds_read2st64_b32 v[30:31], v113 offset0:20 offset1:22
	ds_write2st64_b32 v113, v119, v29 offset0:24 offset1:26
	s_waitcnt lgkmcnt(1)
	v_add_f32_e32 v29, v119, v31
	v_add_f32_e32 v119, v29, v30
	ds_read2st64_b32 v[30:31], v113 offset0:16 offset1:18
	ds_write2st64_b32 v113, v119, v29 offset0:20 offset1:22
	s_waitcnt lgkmcnt(1)
	v_add_f32_e32 v29, v119, v31
	v_add_f32_e32 v119, v29, v30
	ds_read2st64_b32 v[30:31], v113 offset0:12 offset1:14
	ds_write2st64_b32 v113, v119, v29 offset0:16 offset1:18
	s_waitcnt lgkmcnt(1)
	v_add_f32_e32 v29, v119, v31
	v_add_f32_e32 v119, v29, v30
	ds_read2st64_b32 v[30:31], v113 offset0:8 offset1:10
	ds_write2st64_b32 v113, v119, v29 offset0:12 offset1:14
	s_waitcnt lgkmcnt(1)
	v_add_f32_e32 v29, v119, v31
	v_add_f32_e32 v119, v29, v30
	ds_read2st64_b32 v[30:31], v113 offset0:4 offset1:6
	ds_write2st64_b32 v113, v119, v29 offset0:8 offset1:10
	s_waitcnt lgkmcnt(1)
	v_add_f32_e32 v29, v119, v31
	v_add_f32_e32 v119, v29, v30
	ds_read2st64_b32 v[30:31], v113 offset1:2
	ds_write2st64_b32 v113, v119, v29 offset0:4 offset1:6
	s_waitcnt lgkmcnt(1)
	v_add_f32_e32 v29, v119, v31
	v_add_f32_e32 v30, v29, v30
	ds_write2st64_b32 v113, v30, v29 offset1:2

.LBB0_754:
	s_and_b64 vcc, exec, s[0:1]
	s_cbranch_vccz .LBB0_735
	v_cvt_f32_u32_e32 v16, s95
	v_fmaak_f32 v16, 0.5, v16, 0x40a00000
	v_sub_f32_e64 v16, -v16, v96
	v_cmp_gt_f32_e32 vcc, s29, v16
	s_and_b64 s[0:1], vcc, exec
	s_cselect_b32 s0, 0xffffffc0, 0
	v_cndmask_b32_e32 v17, 0, v232, vcc
	v_add_f32_e32 v16, v16, v17
	v_exp_f32_e32 v16, v16
	s_nop 0
	v_ldexp_f32 v111, v16, s0
	v_sub_f32_e32 v18, 1.0, v111
	v_frexp_mant_f32_e32 v20, v18
	v_cvt_f64_f32_e32 v[16:17], v18
	v_frexp_exp_i32_f64_e32 v16, v[16:17]
	v_cmp_gt_f32_e32 vcc, s30, v20
	v_add_f32_e32 v19, -1.0, v18
	v_sub_f32_e32 v21, v19, v18
	v_subbrev_co_u32_e32 v24, vcc, 0, v16, vcc
	v_sub_u32_e32 v16, 0, v24
	v_sub_f32_e64 v19, -v111, v19
	v_add_f32_e32 v21, 1.0, v21
	v_ldexp_f32 v17, v18, v16
	v_add_f32_e32 v19, v19, v21
	v_add_f32_e32 v18, -1.0, v17
	v_add_f32_e32 v20, 1.0, v17
	v_ldexp_f32 v16, v19, v16
	v_add_f32_e32 v19, 1.0, v18
	v_add_f32_e32 v21, -1.0, v20
	v_sub_f32_e32 v19, v17, v19
	v_sub_f32_e32 v17, v17, v21
	v_add_f32_e32 v19, v16, v19
	v_add_f32_e32 v16, v16, v17
	v_add_f32_e32 v25, v20, v16
	v_rcp_f32_e32 v27, v25
	v_sub_f32_e32 v17, v25, v20
	v_sub_f32_e32 v26, v16, v17
	v_add_f32_e32 v17, v18, v19
	v_mul_f32_e32 v29, v17, v27
	v_sub_f32_e32 v16, v17, v18
	v_mul_f32_e32 v18, v25, v29
	v_fma_f32 v20, v29, v25, -v18
	v_fmac_f32_e32 v20, v29, v26
	v_sub_f32_e32 v28, v19, v16
	v_add_f32_e32 v16, v18, v20
	v_sub_f32_e32 v19, v17, v16
	v_pk_add_f32 v[22:23], v[16:17], v[18:19] neg_lo:[0,1] neg_hi:[0,1]
	v_mov_b32_e32 v21, v16
	v_pk_add_f32 v[16:17], v[22:23], v[20:21] neg_lo:[0,1] neg_hi:[0,1]
	v_cmp_nlt_f32_e32 vcc, 1.0, v111
	v_add_f32_e32 v17, v28, v17
	v_add_f32_e32 v16, v16, v17
	v_add_f32_e32 v17, v19, v16
	v_mul_f32_e32 v28, v27, v17
	v_mul_f32_e32 v18, v25, v28
	v_fma_f32 v20, v28, v25, -v18
	v_fmac_f32_e32 v20, v28, v26
	v_sub_f32_e32 v19, v19, v17
	v_add_f32_e32 v25, v16, v19
	v_add_f32_e32 v16, v18, v20
	v_sub_f32_e32 v19, v17, v16
	v_pk_add_f32 v[22:23], v[16:17], v[18:19] neg_lo:[0,1] neg_hi:[0,1]
	v_mov_b32_e32 v21, v16
	v_pk_add_f32 v[16:17], v[22:23], v[20:21] neg_lo:[0,1] neg_hi:[0,1]
	s_nop 0
	v_add_f32_e32 v17, v25, v17
	v_add_f32_e32 v16, v16, v17
	v_add_f32_e32 v17, v29, v28
	v_add_f32_e32 v16, v19, v16
	v_sub_f32_e32 v18, v17, v29
	v_mul_f32_e32 v16, v27, v16
	v_sub_f32_e32 v18, v28, v18
	v_add_f32_e32 v18, v18, v16
	v_add_f32_e32 v20, v17, v18
	v_mul_f32_e32 v21, v20, v20
	v_fmamk_f32 v16, v21, 0x3e9b6dac, v199
	v_fmaak_f32 v193, v21, v16, 0x3f2aaada
	v_cvt_f32_i32_e32 v16, v24
	v_sub_f32_e32 v17, v20, v17
	v_sub_f32_e32 v17, v18, v17
	v_ldexp_f32 v22, v17, 1
	v_mul_f32_e32 v17, v20, v21
	v_ldexp_f32 v19, v20, 1
	v_pk_mul_f32 v[20:21], v[16:17], v[192:193]
	s_nop 0
	v_fma_f32 v18, v16, s31, -v20
	v_fmac_f32_e32 v18, 0xb102e308, v16
	v_pk_add_f32 v[16:17], v[20:21], v[18:19]
	s_nop 0
	v_sub_f32_e32 v19, v17, v19
	v_sub_f32_e32 v19, v21, v19
	v_add_f32_e32 v23, v22, v19
	v_mov_b32_e32 v22, v20
	v_pk_add_f32 v[20:21], v[16:17], v[20:21] neg_lo:[0,1] neg_hi:[0,1]
	v_pk_add_f32 v[24:25], v[16:17], v[22:23]
	v_mov_b32_e32 v19, v16
	v_mov_b32_e32 v21, v25
	v_pk_add_f32 v[26:27], v[18:19], v[20:21] neg_lo:[0,1] neg_hi:[0,1]
	v_pk_add_f32 v[18:19], v[18:19], v[20:21]
	v_mov_b32_e32 v30, v17
	v_pk_add_f32 v[20:21], v[18:19], v[16:17] op_sel:[1,0] op_sel_hi:[0,1] neg_lo:[0,1] neg_hi:[0,1]
	v_pk_add_f32 v[28:29], v[24:25], v[20:21] op_sel_hi:[1,0] neg_lo:[0,1] neg_hi:[0,1]
	v_mov_b32_e32 v24, v25
	v_mov_b32_e32 v25, v19
	v_mov_b32_e32 v31, v20
	v_pk_add_f32 v[20:21], v[24:25], v[30:31] neg_lo:[0,1] neg_hi:[0,1]
	v_mov_b32_e32 v22, v23
	v_mov_b32_e32 v23, v16
	v_pk_add_f32 v[16:17], v[22:23], v[20:21] neg_lo:[0,1] neg_hi:[0,1]
	v_mov_b32_e32 v28, v26
	v_pk_add_f32 v[20:21], v[28:29], v[16:17]
	v_mov_b32_e32 v27, v19
	v_pk_add_f32 v[22:23], v[20:21], v[20:21] op_sel:[0,1] op_sel_hi:[1,0]
	s_nop 0
	v_pk_add_f32 v[18:19], v[18:19], v[22:23] op_sel:[1,0] op_sel_hi:[0,1]
	v_mov_b32_e32 v21, v18
	v_pk_add_f32 v[24:25], v[20:21], v[26:27] neg_lo:[0,1] neg_hi:[0,1]
	v_mov_b32_e32 v17, v22
	v_sub_f32_e32 v19, v20, v24
	v_pk_add_f32 v[16:17], v[16:17], v[24:25] neg_lo:[0,1] neg_hi:[0,1]
	v_sub_f32_e32 v19, v26, v19
	v_add_f32_e32 v16, v16, v19
	v_add_f32_e32 v16, v16, v17
	v_add_f32_e32 v16, v18, v16
	v_sub_u32_e32 v17, 64, v110
	v_add_u32_e32 v18, 1, v110
	v_cndmask_b32_e64 v17, v17, v18, s[92:93]
	v_cvt_f32_i32_e32 v17, v17
	v_cndmask_b32_e32 v16, v233, v16, vcc
	v_cmp_neq_f32_e32 vcc, 1.0, v111
	s_nop 1
	v_cndmask_b32_e32 v16, v234, v16, vcc
	v_cmp_gt_f32_e32 vcc, s34, v111
	s_nop 1
	v_cndmask_b32_e64 v16, v16, -v111, vcc
	v_mul_f32_e32 v16, v16, v17
	v_mov_b32_e32 v17, v16
	v_mov_b32_e32 v18, v16
	v_mov_b32_e32 v19, v16
	ds_write_b128 v109, v[16:19]
	ds_write_b128 v109, v[16:19] offset:16
	ds_write_b128 v109, v[16:19] offset:32
	ds_write_b128 v109, v[16:19] offset:48
	s_waitcnt lgkmcnt(0)
	s_barrier
	s_waitcnt vmcnt(0)
	v_mov_b32_e32 v20, v180
	v_mov_b32_e32 v21, v181
	v_mov_b32_e32 v22, v182
	v_mov_b32_e32 v23, v183
	v_mov_b32_e32 v28, v184
	v_mov_b32_e32 v29, v185
	v_mov_b32_e32 v30, v186
	v_mov_b32_e32 v31, v187
	v_lshlrev_b32_e32 v16, 16, v20
	v_and_b32_e32 v17, 0xffff0000, v20
	v_lshlrev_b32_e32 v18, 16, v21
	v_and_b32_e32 v19, 0xffff0000, v21
	v_lshlrev_b32_e32 v20, 16, v22
	v_and_b32_e32 v21, 0xffff0000, v22
	v_lshlrev_b32_e32 v22, 16, v23
	v_and_b32_e32 v23, 0xffff0000, v23
	v_lshlrev_b32_e32 v24, 16, v28
	v_and_b32_e32 v25, 0xffff0000, v28
	v_lshlrev_b32_e32 v26, 16, v29
	v_and_b32_e32 v27, 0xffff0000, v29
	v_lshlrev_b32_e32 v28, 16, v30
	v_and_b32_e32 v29, 0xffff0000, v30
	v_lshlrev_b32_e32 v30, 16, v31
	v_and_b32_e32 v31, 0xffff0000, v31
	s_branch .LBB0_735
